# H (SwiGLU output) stores in the P7/P9 epilogues marked nt (streaming) so they do not displace GEMM operands in L2
# speedup vs baseline: 1.0038x; 1.0038x over previous
; DI unsigned pk2(float lo, float hi) { f32x2_t v = {lo, hi}; bf16x2_t b = __builtin_convertvector(v, bf16x2_t); return __builtin_bit_cast(unsigned, b); }
; DI float sigmoidf_(float x) { return 1.0f / (1.0f + __expf(-x)); }
;     DI void operator()(AccRef acc, const Unit& u, int wr, int wc, int fr, int fq) const {
;     ...
;                 const int row = row0 + ai * HALF + m * 16; const float rs = rsqrtf(SS1[row] * (1.0f / DM) + EPSN);
;                 float h[8];
; #pragma unroll
;                 for (int n = 0; n < 2; ++n)
; #pragma unroll
;                     for (int e = 0; e < 4; ++e) { const float g = acc[ai][0][m][n][e] * rs, up = acc[ai][1][m][n][e] * rs; h[4 * n + e] = g * sigmoidf_(g) * up; }
;                 u32x4 w; w.x = pk2(h[0], h[1]); w.y = pk2(h[2], h[3]); w.z = pk2(h[4], h[5]); w.w = pk2(h[6], h[7]);
;                 *(u32x4*)(H + (size_t)row * DFF + col0) = w;
.Lp7_hb_done:
	v_mov_b64_e32 v[112:113], s[98:99]
	v_cvt_pk_bf16_f32 v116, v120, v121
	v_cvt_pk_bf16_f32 v119, v114, v115
	v_mad_i64_i32 v[120:121], s[0:1], v144, s44, v[112:113]
	v_lshlrev_b64 v[114:115], 1, v[152:153]
	v_cvt_pk_bf16_f32 v117, v122, v123
	v_lshl_add_u64 v[120:121], v[120:121], 0, v[114:115]
	global_store_dwordx4 v[120:121], v[116:119], off nt
	s_nop 1
	v_or_b32_e32 v116, 16, v144
	v_ashrrev_i32_e32 v117, 31, v116
	v_lshl_add_u64 v[118:119], v[116:117], 2, s[46:47]
	s_nop 0
	s_nop 0
	v_fmamk_f32 v117, v248, 0x3a800000, v158
	v_mul_f32_e32 v118, 0x4b800000, v117
	v_cmp_gt_f32_e32 vcc, s43, v117
	s_nop 1
	v_cndmask_b32_e32 v117, v117, v118, vcc
	v_rsq_f32_e32 v117, v117
	s_nop 0
	v_mul_f32_e32 v118, 0x45800000, v117
	v_cndmask_b32_e32 v118, v117, v118, vcc
	v_pk_mul_f32 v[108:109], v[108:109], v[118:119] op_sel_hi:[1,0]
	v_pk_mul_f32 v[110:111], v[110:111], v[118:119] op_sel_hi:[1,0]
	v_mul_f32_e32 v117, 0xbfb8aa3b, v108
	v_mul_f32_e32 v119, 0xbfb8aa3b, v109
	v_exp_f32_e32 v120, v117
	v_exp_f32_e32 v121, v119
	v_mul_f32_e32 v122, 0xbfb8aa3b, v110
	v_mul_f32_e32 v123, 0xbfb8aa3b, v111
	v_exp_f32_e32 v122, v122
	v_pk_add_f32 v[120:121], v[120:121], 1.0 op_sel_hi:[1,0]
	v_exp_f32_e32 v123, v123
	s_nop 0
	v_pk_add_f32 v[122:123], v[122:123], 1.0 op_sel_hi:[1,0]
	v_pk_mul_f32 v[104:105], v[104:105], v[118:119] op_sel_hi:[1,0]
	v_pk_mul_f32 v[106:107], v[106:107], v[118:119] op_sel_hi:[1,0]
	v_rcp_f32_e32 v121, v121
	v_rcp_f32_e32 v120, v120
	s_nop 0
	v_pk_mul_f32 v[108:109], v[108:109], v[120:121]
	v_pk_mul_f32 v[104:105], v[104:105], v[108:109]
	v_rcp_f32_e32 v109, v123
	v_pk_mul_f32 v[100:101], v[100:101], v[118:119] op_sel_hi:[1,0]
	v_mul_f32_e32 v117, 0xbfb8aa3b, v100
	v_exp_f32_e32 v120, v117
	v_mul_f32_e32 v117, 0xbfb8aa3b, v101
	v_exp_f32_e32 v121, v117
	v_rcp_f32_e32 v108, v122
	s_nop 0
	v_pk_mul_f32 v[108:109], v[110:111], v[108:109]
	v_pk_add_f32 v[120:121], v[120:121], 1.0 op_sel_hi:[1,0]
	v_pk_mul_f32 v[106:107], v[106:107], v[108:109]
	s_nop 0
	v_pk_mul_f32 v[96:97], v[96:97], v[118:119] op_sel_hi:[1,0]
	v_rcp_f32_e32 v109, v121
	v_pk_mul_f32 v[102:103], v[102:103], v[118:119] op_sel_hi:[1,0]
	v_mul_f32_e32 v110, 0xbfb8aa3b, v102
	v_mul_f32_e32 v111, 0xbfb8aa3b, v103
	v_exp_f32_e32 v110, v110
	v_exp_f32_e32 v111, v111
	v_rcp_f32_e32 v108, v120
	s_nop 0
	v_pk_mul_f32 v[100:101], v[100:101], v[108:109]
	v_pk_add_f32 v[110:111], v[110:111], 1.0 op_sel_hi:[1,0]
	v_pk_mul_f32 v[100:101], v[96:97], v[100:101]
	s_nop 0
	v_pk_mul_f32 v[96:97], v[98:99], v[118:119] op_sel_hi:[1,0]
	v_rcp_f32_e32 v99, v111
	v_rcp_f32_e32 v98, v110
	s_nop 0
	v_pk_mul_f32 v[98:99], v[102:103], v[98:99]
	s_nop 0
	v_pk_mul_f32 v[102:103], v[96:97], v[98:99]
	v_cvt_pk_bf16_f32 v98, v100, v101
	v_mad_i64_i32 v[100:101], s[0:1], v116, s44, v[112:113]
	v_cvt_pk_bf16_f32 v96, v104, v105
	v_cvt_pk_bf16_f32 v97, v106, v107
	v_cvt_pk_bf16_f32 v99, v102, v103
	v_lshl_add_u64 v[100:101], v[100:101], 0, v[114:115]
	global_store_dwordx4 v[100:101], v[96:99], off nt
	s_nop 1
	v_or_b32_e32 v96, 32, v144
	v_ashrrev_i32_e32 v97, 31, v96
	v_lshl_add_u64 v[98:99], v[96:97], 2, s[46:47]
	s_nop 0
	s_nop 0
	v_fmamk_f32 v97, v249, 0x3a800000, v158
	v_mul_f32_e32 v98, 0x4b800000, v97
	v_cmp_gt_f32_e32 vcc, s43, v97
	s_nop 1
	v_cndmask_b32_e32 v97, v97, v98, vcc
	v_rsq_f32_e32 v97, v97
	s_nop 0
	v_mul_f32_e32 v98, 0x45800000, v97
	v_cndmask_b32_e32 v98, v97, v98, vcc
	v_pk_mul_f32 v[92:93], v[92:93], v[98:99] op_sel_hi:[1,0]
	s_nop 0
	v_mul_f32_e32 v97, 0xbfb8aa3b, v92
	v_exp_f32_e32 v100, v97
	v_mul_f32_e32 v97, 0xbfb8aa3b, v93
	v_exp_f32_e32 v101, v97
	s_nop 0
	v_pk_add_f32 v[100:101], v[100:101], 1.0 op_sel_hi:[1,0]
	s_nop 0
	s_nop 0
	v_pk_mul_f32 v[88:89], v[88:89], v[98:99] op_sel_hi:[1,0]
	v_rcp_f32_e32 v101, v101
	v_pk_mul_f32 v[94:95], v[94:95], v[98:99] op_sel_hi:[1,0]
	v_mul_f32_e32 v102, 0xbfb8aa3b, v94
	v_mul_f32_e32 v103, 0xbfb8aa3b, v95
	v_exp_f32_e32 v102, v102
	v_exp_f32_e32 v103, v103
	v_rcp_f32_e32 v100, v100
	s_nop 0
	v_pk_mul_f32 v[92:93], v[92:93], v[100:101]
	v_pk_add_f32 v[102:103], v[102:103], 1.0 op_sel_hi:[1,0]
	v_pk_mul_f32 v[88:89], v[88:89], v[92:93]
	s_nop 0
	v_pk_mul_f32 v[90:91], v[90:91], v[98:99] op_sel_hi:[1,0]
	v_rcp_f32_e32 v93, v103
	v_pk_mul_f32 v[84:85], v[84:85], v[98:99] op_sel_hi:[1,0]
	v_mul_f32_e32 v97, 0xbfb8aa3b, v84
	v_exp_f32_e32 v100, v97
	v_mul_f32_e32 v97, 0xbfb8aa3b, v85
	v_exp_f32_e32 v101, v97
	v_rcp_f32_e32 v92, v102
	s_nop 0
	v_pk_mul_f32 v[92:93], v[94:95], v[92:93]
	v_pk_add_f32 v[100:101], v[100:101], 1.0 op_sel_hi:[1,0]
	v_pk_mul_f32 v[90:91], v[90:91], v[92:93]
	s_nop 0
	v_pk_mul_f32 v[80:81], v[80:81], v[98:99] op_sel_hi:[1,0]
	v_rcp_f32_e32 v93, v101
	v_pk_mul_f32 v[86:87], v[86:87], v[98:99] op_sel_hi:[1,0]
	v_mul_f32_e32 v94, 0xbfb8aa3b, v86
	v_mul_f32_e32 v95, 0xbfb8aa3b, v87
	v_exp_f32_e32 v94, v94
	v_exp_f32_e32 v95, v95
	v_rcp_f32_e32 v92, v100
	s_nop 0
	v_pk_mul_f32 v[84:85], v[84:85], v[92:93]
	v_pk_add_f32 v[94:95], v[94:95], 1.0 op_sel_hi:[1,0]
	v_pk_mul_f32 v[84:85], v[80:81], v[84:85]
	s_nop 0
	v_pk_mul_f32 v[80:81], v[82:83], v[98:99] op_sel_hi:[1,0]
	v_rcp_f32_e32 v83, v95
	v_rcp_f32_e32 v82, v94
	s_nop 0
	v_pk_mul_f32 v[82:83], v[86:87], v[82:83]
	s_nop 0
	v_pk_mul_f32 v[86:87], v[80:81], v[82:83]
	v_cvt_pk_bf16_f32 v82, v84, v85
	v_mad_i64_i32 v[84:85], s[0:1], v96, s44, v[112:113]
	v_cvt_pk_bf16_f32 v80, v88, v89
	v_cvt_pk_bf16_f32 v81, v90, v91
	v_cvt_pk_bf16_f32 v83, v86, v87
	v_lshl_add_u64 v[84:85], v[84:85], 0, v[114:115]
	global_store_dwordx4 v[84:85], v[80:83], off nt
	s_nop 1
	v_or_b32_e32 v80, 48, v144
	v_ashrrev_i32_e32 v81, 31, v80
	v_lshl_add_u64 v[82:83], v[80:81], 2, s[46:47]
; DI unsigned pk2(float lo, float hi) { f32x2_t v = {lo, hi}; bf16x2_t b = __builtin_convertvector(v, bf16x2_t); return __builtin_bit_cast(unsigned, b); }
; DI float sigmoidf_(float x) { return 1.0f / (1.0f + __expf(-x)); }
;     DI void operator()(AccRef acc, const Unit& u, int wr, int wc, int fr, int fq) const {
;     ...
;                 const int row = row0 + ai * HALF + m * 16; const float rs = rsqrtf(SS1[row] * (1.0f / DM) + EPSN);
;                 float h[8];
; #pragma unroll
;                 for (int n = 0; n < 2; ++n)
; #pragma unroll
;                     for (int e = 0; e < 4; ++e) { const float g = acc[ai][0][m][n][e] * rs, up = acc[ai][1][m][n][e] * rs; h[4 * n + e] = g * sigmoidf_(g) * up; }
;                 u32x4 w; w.x = pk2(h[0], h[1]); w.y = pk2(h[2], h[3]); w.z = pk2(h[4], h[5]); w.w = pk2(h[6], h[7]);
;                 *(u32x4*)(H + (size_t)row * DFF + col0) = w;
	s_nop 0
	s_nop 0
	v_fmamk_f32 v81, v250, 0x3a800000, v158
	v_mul_f32_e32 v82, 0x4b800000, v81
	v_cmp_gt_f32_e32 vcc, s43, v81
	s_nop 1
	v_cndmask_b32_e32 v81, v81, v82, vcc
	v_rsq_f32_e32 v81, v81
	s_nop 0
	v_mul_f32_e32 v82, 0x45800000, v81
	v_cndmask_b32_e32 v82, v81, v82, vcc
	v_pk_mul_f32 v[76:77], v[76:77], v[82:83] op_sel_hi:[1,0]
	s_nop 0
	v_mul_f32_e32 v81, 0xbfb8aa3b, v76
	v_exp_f32_e32 v84, v81
	v_mul_f32_e32 v81, 0xbfb8aa3b, v77
	v_exp_f32_e32 v85, v81
	s_nop 0
	v_pk_add_f32 v[84:85], v[84:85], 1.0 op_sel_hi:[1,0]
	s_nop 0
	s_nop 0
	v_pk_mul_f32 v[72:73], v[72:73], v[82:83] op_sel_hi:[1,0]
	v_rcp_f32_e32 v85, v85
	v_pk_mul_f32 v[78:79], v[78:79], v[82:83] op_sel_hi:[1,0]
	v_mul_f32_e32 v86, 0xbfb8aa3b, v78
	v_mul_f32_e32 v87, 0xbfb8aa3b, v79
	v_exp_f32_e32 v86, v86
	v_exp_f32_e32 v87, v87
	v_rcp_f32_e32 v84, v84
	s_nop 0
	v_pk_mul_f32 v[76:77], v[76:77], v[84:85]
	v_pk_add_f32 v[86:87], v[86:87], 1.0 op_sel_hi:[1,0]
	v_pk_mul_f32 v[72:73], v[72:73], v[76:77]
	s_nop 0
	v_pk_mul_f32 v[74:75], v[74:75], v[82:83] op_sel_hi:[1,0]
	v_rcp_f32_e32 v77, v87
	v_pk_mul_f32 v[68:69], v[68:69], v[82:83] op_sel_hi:[1,0]
	v_mul_f32_e32 v81, 0xbfb8aa3b, v68
	v_exp_f32_e32 v84, v81
	v_mul_f32_e32 v81, 0xbfb8aa3b, v69
	v_exp_f32_e32 v85, v81
	v_rcp_f32_e32 v76, v86
	s_nop 0
	v_pk_mul_f32 v[76:77], v[78:79], v[76:77]
	v_pk_add_f32 v[84:85], v[84:85], 1.0 op_sel_hi:[1,0]
	v_pk_mul_f32 v[74:75], v[74:75], v[76:77]
	s_nop 0
	v_pk_mul_f32 v[64:65], v[64:65], v[82:83] op_sel_hi:[1,0]
	v_rcp_f32_e32 v77, v85
	v_pk_mul_f32 v[70:71], v[70:71], v[82:83] op_sel_hi:[1,0]
	v_mul_f32_e32 v78, 0xbfb8aa3b, v70
	v_mul_f32_e32 v79, 0xbfb8aa3b, v71
	v_exp_f32_e32 v78, v78
	v_exp_f32_e32 v79, v79
	v_rcp_f32_e32 v76, v84
	s_nop 0
	v_pk_mul_f32 v[68:69], v[68:69], v[76:77]
	v_pk_add_f32 v[78:79], v[78:79], 1.0 op_sel_hi:[1,0]
	v_pk_mul_f32 v[68:69], v[64:65], v[68:69]
	s_nop 0
	v_pk_mul_f32 v[64:65], v[66:67], v[82:83] op_sel_hi:[1,0]
	v_rcp_f32_e32 v67, v79
	v_rcp_f32_e32 v66, v78
	s_nop 0
	v_pk_mul_f32 v[66:67], v[70:71], v[66:67]
	s_nop 0
	v_pk_mul_f32 v[70:71], v[64:65], v[66:67]
	v_cvt_pk_bf16_f32 v66, v68, v69
	v_mad_i64_i32 v[68:69], s[0:1], v80, s44, v[112:113]
	v_cvt_pk_bf16_f32 v64, v72, v73
	v_cvt_pk_bf16_f32 v65, v74, v75
	v_cvt_pk_bf16_f32 v67, v70, v71
	v_lshl_add_u64 v[68:69], v[68:69], 0, v[114:115]
	global_store_dwordx4 v[68:69], v[64:67], off nt
	s_nop 0
	v_add_u32_e32 v70, 0x80, v144
	s_nop 0
	v_fmamk_f32 v64, v251, 0x3a800000, v158
	v_mul_f32_e32 v65, 0x4b800000, v64
	v_cmp_gt_f32_e32 vcc, s43, v64
	s_nop 1
	v_cndmask_b32_e32 v64, v64, v65, vcc
	v_rsq_f32_e32 v64, v64
	s_nop 0
	v_mul_f32_e32 v65, 0x45800000, v64
	v_cndmask_b32_e32 v64, v64, v65, vcc
	v_pk_mul_f32 v[60:61], v[60:61], v[64:65] op_sel_hi:[1,0]
	s_nop 0
	v_mul_f32_e32 v65, 0xbfb8aa3b, v60
	v_exp_f32_e32 v66, v65
	v_mul_f32_e32 v65, 0xbfb8aa3b, v61
	v_exp_f32_e32 v67, v65
	s_nop 0
	v_pk_add_f32 v[66:67], v[66:67], 1.0 op_sel_hi:[1,0]
	s_nop 0
	v_pk_mul_f32 v[56:57], v[56:57], v[64:65] op_sel_hi:[1,0]
	v_rcp_f32_e32 v67, v67
	v_pk_mul_f32 v[62:63], v[62:63], v[64:65] op_sel_hi:[1,0]
	v_mul_f32_e32 v68, 0xbfb8aa3b, v62
	v_mul_f32_e32 v69, 0xbfb8aa3b, v63
	v_exp_f32_e32 v68, v68
	v_exp_f32_e32 v69, v69
	v_rcp_f32_e32 v66, v66
	s_nop 0
	v_pk_mul_f32 v[60:61], v[60:61], v[66:67]
	v_pk_add_f32 v[68:69], v[68:69], 1.0 op_sel_hi:[1,0]
	s_nop 0
	v_pk_mul_f32 v[56:57], v[56:57], v[60:61]
	v_pk_mul_f32 v[58:59], v[58:59], v[64:65] op_sel_hi:[1,0]
	v_rcp_f32_e32 v61, v69
	v_pk_mul_f32 v[52:53], v[52:53], v[64:65] op_sel_hi:[1,0]
	v_mul_f32_e32 v65, 0xbfb8aa3b, v52
	v_exp_f32_e32 v66, v65
	v_mul_f32_e32 v65, 0xbfb8aa3b, v53
	v_exp_f32_e32 v67, v65
	v_rcp_f32_e32 v60, v68
	s_nop 0
	v_pk_mul_f32 v[60:61], v[62:63], v[60:61]
	v_pk_add_f32 v[66:67], v[66:67], 1.0 op_sel_hi:[1,0]
	v_pk_mul_f32 v[58:59], v[58:59], v[60:61]
	v_pk_mul_f32 v[48:49], v[48:49], v[64:65] op_sel_hi:[1,0]
	v_rcp_f32_e32 v61, v67
	v_pk_mul_f32 v[54:55], v[54:55], v[64:65] op_sel_hi:[1,0]
	v_mul_f32_e32 v62, 0xbfb8aa3b, v54
	v_mul_f32_e32 v63, 0xbfb8aa3b, v55
	v_exp_f32_e32 v62, v62
	v_exp_f32_e32 v63, v63
	v_rcp_f32_e32 v60, v66
	s_nop 0
	v_pk_mul_f32 v[52:53], v[52:53], v[60:61]
	v_pk_add_f32 v[62:63], v[62:63], 1.0 op_sel_hi:[1,0]
	v_pk_mul_f32 v[52:53], v[48:49], v[52:53]
	v_pk_mul_f32 v[48:49], v[50:51], v[64:65] op_sel_hi:[1,0]
	v_rcp_f32_e32 v51, v63
	v_rcp_f32_e32 v50, v62
	s_nop 0
	v_pk_mul_f32 v[50:51], v[54:55], v[50:51]
	s_nop 0
	v_pk_mul_f32 v[54:55], v[48:49], v[50:51]
	v_cvt_pk_bf16_f32 v50, v52, v53
	v_mad_i64_i32 v[52:53], s[0:1], v70, s44, v[112:113]
	v_cvt_pk_bf16_f32 v48, v56, v57
	v_cvt_pk_bf16_f32 v49, v58, v59
	v_cvt_pk_bf16_f32 v51, v54, v55
	v_lshl_add_u64 v[52:53], v[52:53], 0, v[114:115]
	global_store_dwordx4 v[52:53], v[48:51], off nt
	s_nop 0
	v_add_u32_e32 v54, 0x90, v144
	s_nop 0
	v_fmamk_f32 v48, v252, 0x3a800000, v158
	v_mul_f32_e32 v49, 0x4b800000, v48
	v_cmp_gt_f32_e32 vcc, s43, v48
	s_nop 1
	v_cndmask_b32_e32 v48, v48, v49, vcc
	v_rsq_f32_e32 v48, v48
	s_nop 0
	v_mul_f32_e32 v49, 0x45800000, v48
	v_cndmask_b32_e32 v48, v48, v49, vcc
	v_pk_mul_f32 v[44:45], v[44:45], v[48:49] op_sel_hi:[1,0]
	s_nop 0
	v_mul_f32_e32 v49, 0xbfb8aa3b, v44
	v_exp_f32_e32 v50, v49
	v_mul_f32_e32 v49, 0xbfb8aa3b, v45
	v_exp_f32_e32 v51, v49
	s_nop 0
	v_pk_add_f32 v[50:51], v[50:51], 1.0 op_sel_hi:[1,0]
	s_nop 0
	v_pk_mul_f32 v[40:41], v[40:41], v[48:49] op_sel_hi:[1,0]
	v_rcp_f32_e32 v51, v51
	v_pk_mul_f32 v[46:47], v[46:47], v[48:49] op_sel_hi:[1,0]
	v_mul_f32_e32 v52, 0xbfb8aa3b, v46
	v_mul_f32_e32 v53, 0xbfb8aa3b, v47
	v_exp_f32_e32 v52, v52
	v_exp_f32_e32 v53, v53
	v_rcp_f32_e32 v50, v50
	s_nop 0
; #define PG8_BAR __builtin_amdgcn_s_barrier()
; DI unsigned pk2(float lo, float hi) { f32x2_t v = {lo, hi}; bf16x2_t b = __builtin_convertvector(v, bf16x2_t); return __builtin_bit_cast(unsigned, b); }
; DI float sigmoidf_(float x) { return 1.0f / (1.0f + __expf(-x)); }
; template <class Epi, class Sched, bool ALIGN_EPI = false, bool SP2 = false>
; __device__ __forceinline__ void gemm_phase(PG8_LAS unsigned char* lds, const Gemm g, const Sched& S, const Epi& E) {
;     ...
;         if (!has_next) break;
; #pragma unroll
;         for (int a = 0; a < 2; ++a)
; #pragma unroll
;             for (int b = 0; b < 2; ++b)
; #pragma unroll
;                 for (int m = 0; m < 4; ++m)
; #pragma unroll
;                     for (int n = 0; n < 2; ++n) acc[a][b][m][n] = (f32x4){0.f, 0.f, 0.f, 0.f};
;         cur = nxt; cA = nA; cB = nB; ++ui;
;         if constexpr (ALIGN_EPI) { if (wr == 1) PG8_BAR; }
;     DI void operator()(AccRef acc, const Unit& u, int wr, int wc, int fr, int fq) const {
;     ...
;                 const int row = row0 + ai * HALF + m * 16; const float rs = rsqrtf(SS1[row] * (1.0f / DM) + EPSN);
;                 float h[8];
; #pragma unroll
;                 for (int n = 0; n < 2; ++n)
; #pragma unroll
;                     for (int e = 0; e < 4; ++e) { const float g = acc[ai][0][m][n][e] * rs, up = acc[ai][1][m][n][e] * rs; h[4 * n + e] = g * sigmoidf_(g) * up; }
;                 u32x4 w; w.x = pk2(h[0], h[1]); w.y = pk2(h[2], h[3]); w.z = pk2(h[4], h[5]); w.w = pk2(h[6], h[7]);
;                 *(u32x4*)(H + (size_t)row * DFF + col0) = w;
	v_pk_mul_f32 v[44:45], v[44:45], v[50:51]
	v_pk_add_f32 v[52:53], v[52:53], 1.0 op_sel_hi:[1,0]
	s_nop 0
	v_pk_mul_f32 v[40:41], v[40:41], v[44:45]
	v_pk_mul_f32 v[42:43], v[42:43], v[48:49] op_sel_hi:[1,0]
	v_rcp_f32_e32 v45, v53
	v_pk_mul_f32 v[36:37], v[36:37], v[48:49] op_sel_hi:[1,0]
	v_mul_f32_e32 v49, 0xbfb8aa3b, v36
	v_exp_f32_e32 v50, v49
	v_mul_f32_e32 v49, 0xbfb8aa3b, v37
	v_exp_f32_e32 v51, v49
	v_rcp_f32_e32 v44, v52
	s_nop 0
	v_pk_mul_f32 v[44:45], v[46:47], v[44:45]
	v_pk_add_f32 v[50:51], v[50:51], 1.0 op_sel_hi:[1,0]
	v_pk_mul_f32 v[42:43], v[42:43], v[44:45]
	v_pk_mul_f32 v[32:33], v[32:33], v[48:49] op_sel_hi:[1,0]
	v_rcp_f32_e32 v45, v51
	v_pk_mul_f32 v[38:39], v[38:39], v[48:49] op_sel_hi:[1,0]
	v_mul_f32_e32 v46, 0xbfb8aa3b, v38
	v_mul_f32_e32 v47, 0xbfb8aa3b, v39
	v_exp_f32_e32 v46, v46
	v_exp_f32_e32 v47, v47
	v_rcp_f32_e32 v44, v50
	s_nop 0
	v_pk_mul_f32 v[36:37], v[36:37], v[44:45]
	v_pk_add_f32 v[46:47], v[46:47], 1.0 op_sel_hi:[1,0]
	v_pk_mul_f32 v[36:37], v[32:33], v[36:37]
	v_pk_mul_f32 v[32:33], v[34:35], v[48:49] op_sel_hi:[1,0]
	v_rcp_f32_e32 v35, v47
	v_rcp_f32_e32 v34, v46
	s_nop 0
	v_pk_mul_f32 v[34:35], v[38:39], v[34:35]
	s_nop 0
	v_pk_mul_f32 v[38:39], v[32:33], v[34:35]
	v_cvt_pk_bf16_f32 v34, v36, v37
	v_mad_i64_i32 v[36:37], s[0:1], v54, s44, v[112:113]
	v_cvt_pk_bf16_f32 v32, v40, v41
	v_cvt_pk_bf16_f32 v33, v42, v43
	v_cvt_pk_bf16_f32 v35, v38, v39
	v_lshl_add_u64 v[36:37], v[36:37], 0, v[114:115]
	global_store_dwordx4 v[36:37], v[32:35], off nt
	s_nop 0
	v_add_u32_e32 v38, 0xa0, v144
	s_nop 0
	v_fmamk_f32 v32, v253, 0x3a800000, v158
	v_mul_f32_e32 v33, 0x4b800000, v32
	v_cmp_gt_f32_e32 vcc, s43, v32
	s_nop 1
	v_cndmask_b32_e32 v32, v32, v33, vcc
	v_rsq_f32_e32 v32, v32
	s_nop 0
	v_mul_f32_e32 v33, 0x45800000, v32
	v_cndmask_b32_e32 v32, v32, v33, vcc
	v_pk_mul_f32 v[28:29], v[28:29], v[32:33] op_sel_hi:[1,0]
	s_nop 0
	v_mul_f32_e32 v33, 0xbfb8aa3b, v28
	v_exp_f32_e32 v34, v33
	v_mul_f32_e32 v33, 0xbfb8aa3b, v29
	v_exp_f32_e32 v35, v33
	s_nop 0
	v_pk_add_f32 v[34:35], v[34:35], 1.0 op_sel_hi:[1,0]
	s_nop 0
	v_pk_mul_f32 v[24:25], v[24:25], v[32:33] op_sel_hi:[1,0]
	v_rcp_f32_e32 v35, v35
	v_pk_mul_f32 v[30:31], v[30:31], v[32:33] op_sel_hi:[1,0]
	v_mul_f32_e32 v36, 0xbfb8aa3b, v30
	v_mul_f32_e32 v37, 0xbfb8aa3b, v31
	v_exp_f32_e32 v36, v36
	v_exp_f32_e32 v37, v37
	v_rcp_f32_e32 v34, v34
	s_nop 0
	v_pk_mul_f32 v[28:29], v[28:29], v[34:35]
	v_pk_add_f32 v[36:37], v[36:37], 1.0 op_sel_hi:[1,0]
	s_nop 0
	v_pk_mul_f32 v[24:25], v[24:25], v[28:29]
	v_pk_mul_f32 v[26:27], v[26:27], v[32:33] op_sel_hi:[1,0]
	v_rcp_f32_e32 v29, v37
	v_pk_mul_f32 v[20:21], v[20:21], v[32:33] op_sel_hi:[1,0]
	v_mul_f32_e32 v33, 0xbfb8aa3b, v20
	v_exp_f32_e32 v34, v33
	v_mul_f32_e32 v33, 0xbfb8aa3b, v21
	v_exp_f32_e32 v35, v33
	v_rcp_f32_e32 v28, v36
	s_nop 0
	v_pk_mul_f32 v[28:29], v[30:31], v[28:29]
	v_pk_add_f32 v[34:35], v[34:35], 1.0 op_sel_hi:[1,0]
	v_pk_mul_f32 v[26:27], v[26:27], v[28:29]
	v_pk_mul_f32 v[16:17], v[16:17], v[32:33] op_sel_hi:[1,0]
	v_rcp_f32_e32 v29, v35
	v_pk_mul_f32 v[22:23], v[22:23], v[32:33] op_sel_hi:[1,0]
	v_mul_f32_e32 v30, 0xbfb8aa3b, v22
	v_mul_f32_e32 v31, 0xbfb8aa3b, v23
	v_exp_f32_e32 v30, v30
	v_exp_f32_e32 v31, v31
	v_rcp_f32_e32 v28, v34
	s_nop 0
	v_pk_mul_f32 v[20:21], v[20:21], v[28:29]
	v_pk_add_f32 v[30:31], v[30:31], 1.0 op_sel_hi:[1,0]
	v_pk_mul_f32 v[20:21], v[16:17], v[20:21]
	v_pk_mul_f32 v[16:17], v[18:19], v[32:33] op_sel_hi:[1,0]
	v_rcp_f32_e32 v19, v31
	v_rcp_f32_e32 v18, v30
	s_nop 0
	v_pk_mul_f32 v[18:19], v[22:23], v[18:19]
	s_nop 0
	v_pk_mul_f32 v[22:23], v[16:17], v[18:19]
	v_cvt_pk_bf16_f32 v18, v20, v21
	v_mad_i64_i32 v[20:21], s[0:1], v38, s44, v[112:113]
	v_cvt_pk_bf16_f32 v16, v24, v25
	v_cvt_pk_bf16_f32 v17, v26, v27
	v_cvt_pk_bf16_f32 v19, v22, v23
	v_lshl_add_u64 v[20:21], v[20:21], 0, v[114:115]
	global_store_dwordx4 v[20:21], v[16:19], off nt
	s_nop 0
	v_add_u32_e32 v22, 0xb0, v144
	s_nop 0
	v_fmamk_f32 v16, v254, 0x3a800000, v158
	v_mul_f32_e32 v17, 0x4b800000, v16
	v_cmp_gt_f32_e32 vcc, s43, v16
	s_nop 1
	v_cndmask_b32_e32 v16, v16, v17, vcc
	v_rsq_f32_e32 v16, v16
	s_nop 0
	v_mul_f32_e32 v17, 0x45800000, v16
	v_cndmask_b32_e32 v16, v16, v17, vcc
	v_pk_mul_f32 v[12:13], v[12:13], v[16:17] op_sel_hi:[1,0]
	s_nop 0
	v_mul_f32_e32 v17, 0xbfb8aa3b, v12
	v_exp_f32_e32 v18, v17
	v_mul_f32_e32 v17, 0xbfb8aa3b, v13
	v_exp_f32_e32 v19, v17
	s_nop 0
	v_pk_add_f32 v[18:19], v[18:19], 1.0 op_sel_hi:[1,0]
	s_nop 0
	v_pk_mul_f32 v[8:9], v[8:9], v[16:17] op_sel_hi:[1,0]
	v_rcp_f32_e32 v19, v19
	v_pk_mul_f32 v[14:15], v[14:15], v[16:17] op_sel_hi:[1,0]
	v_mul_f32_e32 v20, 0xbfb8aa3b, v14
	v_mul_f32_e32 v21, 0xbfb8aa3b, v15
	v_exp_f32_e32 v20, v20
	v_exp_f32_e32 v21, v21
	v_rcp_f32_e32 v18, v18
	s_nop 0
	v_pk_mul_f32 v[12:13], v[12:13], v[18:19]
	v_pk_add_f32 v[20:21], v[20:21], 1.0 op_sel_hi:[1,0]
	s_nop 0
	v_pk_mul_f32 v[8:9], v[8:9], v[12:13]
	v_pk_mul_f32 v[10:11], v[10:11], v[16:17] op_sel_hi:[1,0]
	v_rcp_f32_e32 v13, v21
	v_pk_mul_f32 v[4:5], v[4:5], v[16:17] op_sel_hi:[1,0]
	v_mul_f32_e32 v17, 0xbfb8aa3b, v4
	v_exp_f32_e32 v18, v17
	v_mul_f32_e32 v17, 0xbfb8aa3b, v5
	v_exp_f32_e32 v19, v17
	v_rcp_f32_e32 v12, v20
	s_nop 0
	v_pk_mul_f32 v[12:13], v[14:15], v[12:13]
	v_pk_add_f32 v[18:19], v[18:19], 1.0 op_sel_hi:[1,0]
	v_pk_mul_f32 v[10:11], v[10:11], v[12:13]
	v_pk_mul_f32 v[0:1], v[0:1], v[16:17] op_sel_hi:[1,0]
	v_rcp_f32_e32 v13, v19
	v_pk_mul_f32 v[6:7], v[6:7], v[16:17] op_sel_hi:[1,0]
	v_mul_f32_e32 v14, 0xbfb8aa3b, v6
	v_mul_f32_e32 v15, 0xbfb8aa3b, v7
	v_exp_f32_e32 v14, v14
	v_exp_f32_e32 v15, v15
	v_rcp_f32_e32 v12, v18
	s_nop 0
	v_pk_mul_f32 v[4:5], v[4:5], v[12:13]
	v_pk_add_f32 v[14:15], v[14:15], 1.0 op_sel_hi:[1,0]
	v_pk_mul_f32 v[4:5], v[0:1], v[4:5]
	v_pk_mul_f32 v[0:1], v[2:3], v[16:17] op_sel_hi:[1,0]
	v_rcp_f32_e32 v3, v15
	v_rcp_f32_e32 v2, v14
	s_nop 0
	v_pk_mul_f32 v[2:3], v[6:7], v[2:3]
	s_andn2_b64 vcc, exec, s[2:3]
	v_pk_mul_f32 v[6:7], v[0:1], v[2:3]
	v_cvt_pk_bf16_f32 v2, v4, v5
	v_mad_i64_i32 v[4:5], s[0:1], v22, s44, v[112:113]
	v_cvt_pk_bf16_f32 v0, v8, v9
	v_cvt_pk_bf16_f32 v1, v10, v11
	v_cvt_pk_bf16_f32 v3, v6, v7
	v_lshl_add_u64 v[4:5], v[4:5], 0, v[114:115]
	s_mov_b64 s[0:1], -1
	global_store_dwordx4 v[4:5], v[0:3], off nt
	s_cbranch_vccnz .LBB0_1483
	s_andn2_b64 vcc, exec, s[14:15]
	s_cbranch_vccnz .LBB0_1482
	s_barrier
	s_branch .LBB0_1482

; DI unsigned pk2(float lo, float hi) { f32x2_t v = {lo, hi}; bf16x2_t b = __builtin_convertvector(v, bf16x2_t); return __builtin_bit_cast(unsigned, b); }
; DI float sigmoidf_(float x) { return 1.0f / (1.0f + __expf(-x)); }
;     DI void operator()(AccRef acc, const Unit& u, int wr, int wc, int fr, int fq) const {
;         const int row0 = u.pm * BM + wr * 64 + fr, col0 = u.pn * 128 + wc * 32 + 8 * fq;
; #pragma unroll
;         for (int ai = 0; ai < 2; ++ai)
; #pragma unroll
;             for (int m = 0; m < 4; ++m) {
;                 const int row = row0 + ai * HALF + m * 16; const float rs = rsqrtf(SS1[row] * (1.0f / DM) + EPSN);
;                 float h[8];
; #pragma unroll
;                 for (int n = 0; n < 2; ++n)
; #pragma unroll
;                     for (int e = 0; e < 4; ++e) { const float g = acc[ai][0][m][n][e] * rs, up = acc[ai][1][m][n][e] * rs; h[4 * n + e] = g * sigmoidf_(g) * up; }
;                 u32x4 w; w.x = pk2(h[0], h[1]); w.y = pk2(h[2], h[3]); w.z = pk2(h[4], h[5]); w.w = pk2(h[6], h[7]);
;                 *(u32x4*)(H + (size_t)row * DFF + col0) = w;
.LBB0_1669:
	v_lshl_add_u32 v144, s0, 8, v149
	v_ashrrev_i32_e32 v145, 31, v144
	v_lshl_add_u64 v[146:147], v[144:145], 2, s[18:19]
	global_load_dword v145, v[146:147], off
	global_load_dword v248, v[146:147], off offset:64
	global_load_dword v249, v[146:147], off offset:128
	global_load_dword v250, v[146:147], off offset:192
	global_load_dword v251, v[146:147], off offset:512
	global_load_dword v252, v[146:147], off offset:576
	global_load_dword v253, v[146:147], off offset:640
	global_load_dword v254, v[146:147], off offset:704
	s_waitcnt vmcnt(0)
	v_fmamk_f32 v145, v145, 0x3a800000, v158
	v_mul_f32_e32 v152, 0x4b800000, v145
	v_cmp_gt_f32_e32 vcc, s51, v145
	s_nop 1
	v_cndmask_b32_e32 v145, v145, v152, vcc
	v_rsq_f32_e32 v145, v145
	v_lshl_or_b32 v152, s1, 7, v154
	v_ashrrev_i32_e32 v153, 31, v152
	v_mul_f32_e32 v159, 0x45800000, v145
	v_cndmask_b32_e32 v160, v145, v159, vcc
	v_pk_mul_f32 v[124:125], v[124:125], v[160:161] op_sel_hi:[1,0]
	v_pk_mul_f32 v[126:127], v[126:127], v[160:161] op_sel_hi:[1,0]
	v_mul_f32_e32 v145, 0xbfb8aa3b, v124
	v_mul_f32_e32 v159, 0xbfb8aa3b, v125
	v_exp_f32_e32 v162, v145
	v_exp_f32_e32 v163, v159
	v_pk_mul_f32 v[120:121], v[120:121], v[160:161] op_sel_hi:[1,0]
	v_pk_mul_f32 v[122:123], v[122:123], v[160:161] op_sel_hi:[1,0]
	v_pk_mul_f32 v[116:117], v[116:117], v[160:161] op_sel_hi:[1,0]
	v_mul_f32_e32 v161, 0xbfb8aa3b, v126
	v_mul_f32_e32 v165, 0xbfb8aa3b, v127
	v_exp_f32_e32 v164, v161
	v_exp_f32_e32 v165, v165
	v_pk_add_f32 v[162:163], v[162:163], 1.0 op_sel_hi:[1,0]
	v_pk_mul_f32 v[112:113], v[112:113], v[160:161] op_sel_hi:[1,0]
	v_pk_add_f32 v[164:165], v[164:165], 1.0 op_sel_hi:[1,0]
	v_mul_f32_e32 v166, 0xbfb8aa3b, v116
	v_mul_f32_e32 v167, 0xbfb8aa3b, v117
	v_exp_f32_e32 v166, v166
	v_exp_f32_e32 v167, v167
	s_nop 0
	v_pk_add_f32 v[166:167], v[166:167], 1.0 op_sel_hi:[1,0]
	v_rcp_f32_e32 v163, v163
	v_rcp_f32_e32 v162, v162
	s_nop 0
	v_pk_mul_f32 v[124:125], v[124:125], v[162:163]
	v_rcp_f32_e32 v163, v165
	v_rcp_f32_e32 v162, v164
	v_pk_mul_f32 v[120:121], v[120:121], v[124:125]
	v_pk_mul_f32 v[124:125], v[126:127], v[162:163]
	v_pk_mul_f32 v[118:119], v[118:119], v[160:161] op_sel_hi:[1,0]
	v_pk_mul_f32 v[122:123], v[122:123], v[124:125]
	v_mul_f32_e32 v124, 0xbfb8aa3b, v118
	v_mul_f32_e32 v125, 0xbfb8aa3b, v119
	v_exp_f32_e32 v124, v124
	v_exp_f32_e32 v125, v125
	s_nop 0
	v_pk_add_f32 v[124:125], v[124:125], 1.0 op_sel_hi:[1,0]
	v_rcp_f32_e32 v127, v167
	v_rcp_f32_e32 v126, v166
	s_nop 0
	v_pk_mul_f32 v[116:117], v[116:117], v[126:127]
	v_pk_mul_f32 v[114:115], v[114:115], v[160:161] op_sel_hi:[1,0]
	v_pk_mul_f32 v[112:113], v[112:113], v[116:117]
	v_rcp_f32_e32 v117, v125
	v_rcp_f32_e32 v116, v124
	s_nop 0
	v_pk_mul_f32 v[116:117], v[118:119], v[116:117]
	v_cvt_pk_bf16_f32 v118, v112, v113
	v_pk_mul_f32 v[114:115], v[114:115], v[116:117]
	v_mov_b64_e32 v[112:113], s[48:49]
	v_cvt_pk_bf16_f32 v116, v120, v121
	v_cvt_pk_bf16_f32 v119, v114, v115
	v_mad_i64_i32 v[120:121], s[0:1], v144, s52, v[112:113]
	v_lshlrev_b64 v[114:115], 1, v[152:153]
	v_cvt_pk_bf16_f32 v117, v122, v123
	v_lshl_add_u64 v[120:121], v[120:121], 0, v[114:115]
	global_store_dwordx4 v[120:121], v[116:119], off nt
	s_nop 1
	v_or_b32_e32 v116, 16, v144
	v_ashrrev_i32_e32 v117, 31, v116
	v_lshl_add_u64 v[118:119], v[116:117], 2, s[18:19]
	s_nop 0
	s_nop 0
	v_fmamk_f32 v117, v248, 0x3a800000, v158
	v_mul_f32_e32 v118, 0x4b800000, v117
	v_cmp_gt_f32_e32 vcc, s51, v117
	s_nop 1
	v_cndmask_b32_e32 v117, v117, v118, vcc
	v_rsq_f32_e32 v117, v117
	s_nop 0
	v_mul_f32_e32 v118, 0x45800000, v117
	v_cndmask_b32_e32 v118, v117, v118, vcc
	v_pk_mul_f32 v[108:109], v[108:109], v[118:119] op_sel_hi:[1,0]
	v_pk_mul_f32 v[110:111], v[110:111], v[118:119] op_sel_hi:[1,0]
	v_mul_f32_e32 v117, 0xbfb8aa3b, v108
	v_mul_f32_e32 v119, 0xbfb8aa3b, v109
	v_exp_f32_e32 v120, v117
	v_exp_f32_e32 v121, v119
	v_mul_f32_e32 v122, 0xbfb8aa3b, v110
	v_mul_f32_e32 v123, 0xbfb8aa3b, v111
	v_exp_f32_e32 v122, v122
	v_pk_add_f32 v[120:121], v[120:121], 1.0 op_sel_hi:[1,0]
	v_exp_f32_e32 v123, v123
	s_nop 0
	v_pk_add_f32 v[122:123], v[122:123], 1.0 op_sel_hi:[1,0]
	v_pk_mul_f32 v[104:105], v[104:105], v[118:119] op_sel_hi:[1,0]
	v_pk_mul_f32 v[106:107], v[106:107], v[118:119] op_sel_hi:[1,0]
	v_rcp_f32_e32 v121, v121
	v_rcp_f32_e32 v120, v120
	s_nop 0
	v_pk_mul_f32 v[108:109], v[108:109], v[120:121]
	v_pk_mul_f32 v[104:105], v[104:105], v[108:109]
	v_rcp_f32_e32 v109, v123
	v_pk_mul_f32 v[100:101], v[100:101], v[118:119] op_sel_hi:[1,0]
	v_mul_f32_e32 v117, 0xbfb8aa3b, v100
	v_exp_f32_e32 v120, v117
	v_mul_f32_e32 v117, 0xbfb8aa3b, v101
	v_exp_f32_e32 v121, v117
	v_rcp_f32_e32 v108, v122
	s_nop 0
	v_pk_mul_f32 v[108:109], v[110:111], v[108:109]
	v_pk_add_f32 v[120:121], v[120:121], 1.0 op_sel_hi:[1,0]
	v_pk_mul_f32 v[106:107], v[106:107], v[108:109]
	s_nop 0
	v_pk_mul_f32 v[96:97], v[96:97], v[118:119] op_sel_hi:[1,0]
	v_rcp_f32_e32 v109, v121
	v_pk_mul_f32 v[102:103], v[102:103], v[118:119] op_sel_hi:[1,0]
	v_mul_f32_e32 v110, 0xbfb8aa3b, v102
	v_mul_f32_e32 v111, 0xbfb8aa3b, v103
	v_exp_f32_e32 v110, v110
	v_exp_f32_e32 v111, v111
	v_rcp_f32_e32 v108, v120
	s_nop 0
	v_pk_mul_f32 v[100:101], v[100:101], v[108:109]
	v_pk_add_f32 v[110:111], v[110:111], 1.0 op_sel_hi:[1,0]
	v_pk_mul_f32 v[100:101], v[96:97], v[100:101]
	s_nop 0
	v_pk_mul_f32 v[96:97], v[98:99], v[118:119] op_sel_hi:[1,0]
	v_rcp_f32_e32 v99, v111
	v_rcp_f32_e32 v98, v110
	s_nop 0
	v_pk_mul_f32 v[98:99], v[102:103], v[98:99]
	s_nop 0
	v_pk_mul_f32 v[102:103], v[96:97], v[98:99]
	v_cvt_pk_bf16_f32 v98, v100, v101
	v_mad_i64_i32 v[100:101], s[0:1], v116, s52, v[112:113]
	v_cvt_pk_bf16_f32 v96, v104, v105
; DI unsigned pk2(float lo, float hi) { f32x2_t v = {lo, hi}; bf16x2_t b = __builtin_convertvector(v, bf16x2_t); return __builtin_bit_cast(unsigned, b); }
; DI float sigmoidf_(float x) { return 1.0f / (1.0f + __expf(-x)); }
;     DI void operator()(AccRef acc, const Unit& u, int wr, int wc, int fr, int fq) const {
;     ...
;                 const int row = row0 + ai * HALF + m * 16; const float rs = rsqrtf(SS1[row] * (1.0f / DM) + EPSN);
;                 float h[8];
; #pragma unroll
;                 for (int n = 0; n < 2; ++n)
; #pragma unroll
;                     for (int e = 0; e < 4; ++e) { const float g = acc[ai][0][m][n][e] * rs, up = acc[ai][1][m][n][e] * rs; h[4 * n + e] = g * sigmoidf_(g) * up; }
;                 u32x4 w; w.x = pk2(h[0], h[1]); w.y = pk2(h[2], h[3]); w.z = pk2(h[4], h[5]); w.w = pk2(h[6], h[7]);
;                 *(u32x4*)(H + (size_t)row * DFF + col0) = w;
	v_cvt_pk_bf16_f32 v97, v106, v107
	v_cvt_pk_bf16_f32 v99, v102, v103
	v_lshl_add_u64 v[100:101], v[100:101], 0, v[114:115]
	global_store_dwordx4 v[100:101], v[96:99], off nt
	s_nop 1
	v_or_b32_e32 v96, 32, v144
	v_ashrrev_i32_e32 v97, 31, v96
	v_lshl_add_u64 v[98:99], v[96:97], 2, s[18:19]
	s_nop 0
	s_nop 0
	v_fmamk_f32 v97, v249, 0x3a800000, v158
	v_mul_f32_e32 v98, 0x4b800000, v97
	v_cmp_gt_f32_e32 vcc, s51, v97
	s_nop 1
	v_cndmask_b32_e32 v97, v97, v98, vcc
	v_rsq_f32_e32 v97, v97
	s_nop 0
	v_mul_f32_e32 v98, 0x45800000, v97
	v_cndmask_b32_e32 v98, v97, v98, vcc
	v_pk_mul_f32 v[92:93], v[92:93], v[98:99] op_sel_hi:[1,0]
	s_nop 0
	v_mul_f32_e32 v97, 0xbfb8aa3b, v92
	v_exp_f32_e32 v100, v97
	v_mul_f32_e32 v97, 0xbfb8aa3b, v93
	v_exp_f32_e32 v101, v97
	s_nop 0
	v_pk_add_f32 v[100:101], v[100:101], 1.0 op_sel_hi:[1,0]
	s_nop 0
	s_nop 0
	v_pk_mul_f32 v[88:89], v[88:89], v[98:99] op_sel_hi:[1,0]
	v_rcp_f32_e32 v101, v101
	v_pk_mul_f32 v[94:95], v[94:95], v[98:99] op_sel_hi:[1,0]
	v_mul_f32_e32 v102, 0xbfb8aa3b, v94
	v_mul_f32_e32 v103, 0xbfb8aa3b, v95
	v_exp_f32_e32 v102, v102
	v_exp_f32_e32 v103, v103
	v_rcp_f32_e32 v100, v100
	s_nop 0
	v_pk_mul_f32 v[92:93], v[92:93], v[100:101]
	v_pk_add_f32 v[102:103], v[102:103], 1.0 op_sel_hi:[1,0]
	v_pk_mul_f32 v[88:89], v[88:89], v[92:93]
	s_nop 0
	v_pk_mul_f32 v[90:91], v[90:91], v[98:99] op_sel_hi:[1,0]
	v_rcp_f32_e32 v93, v103
	v_pk_mul_f32 v[84:85], v[84:85], v[98:99] op_sel_hi:[1,0]
	v_mul_f32_e32 v97, 0xbfb8aa3b, v84
	v_exp_f32_e32 v100, v97
	v_mul_f32_e32 v97, 0xbfb8aa3b, v85
	v_exp_f32_e32 v101, v97
	v_rcp_f32_e32 v92, v102
	s_nop 0
	v_pk_mul_f32 v[92:93], v[94:95], v[92:93]
	v_pk_add_f32 v[100:101], v[100:101], 1.0 op_sel_hi:[1,0]
	v_pk_mul_f32 v[90:91], v[90:91], v[92:93]
	s_nop 0
	v_pk_mul_f32 v[80:81], v[80:81], v[98:99] op_sel_hi:[1,0]
	v_rcp_f32_e32 v93, v101
	v_pk_mul_f32 v[86:87], v[86:87], v[98:99] op_sel_hi:[1,0]
	v_mul_f32_e32 v94, 0xbfb8aa3b, v86
	v_mul_f32_e32 v95, 0xbfb8aa3b, v87
	v_exp_f32_e32 v94, v94
	v_exp_f32_e32 v95, v95
	v_rcp_f32_e32 v92, v100
	s_nop 0
	v_pk_mul_f32 v[84:85], v[84:85], v[92:93]
	v_pk_add_f32 v[94:95], v[94:95], 1.0 op_sel_hi:[1,0]
	v_pk_mul_f32 v[84:85], v[80:81], v[84:85]
	s_nop 0
	v_pk_mul_f32 v[80:81], v[82:83], v[98:99] op_sel_hi:[1,0]
	v_rcp_f32_e32 v83, v95
	v_rcp_f32_e32 v82, v94
	s_nop 0
	v_pk_mul_f32 v[82:83], v[86:87], v[82:83]
	s_nop 0
	v_pk_mul_f32 v[86:87], v[80:81], v[82:83]
	v_cvt_pk_bf16_f32 v82, v84, v85
	v_mad_i64_i32 v[84:85], s[0:1], v96, s52, v[112:113]
	v_cvt_pk_bf16_f32 v80, v88, v89
	v_cvt_pk_bf16_f32 v81, v90, v91
	v_cvt_pk_bf16_f32 v83, v86, v87
	v_lshl_add_u64 v[84:85], v[84:85], 0, v[114:115]
	global_store_dwordx4 v[84:85], v[80:83], off nt
	s_nop 1
	v_or_b32_e32 v80, 48, v144
	v_ashrrev_i32_e32 v81, 31, v80
	v_lshl_add_u64 v[82:83], v[80:81], 2, s[18:19]
	s_nop 0
	s_nop 0
	v_fmamk_f32 v81, v250, 0x3a800000, v158
	v_mul_f32_e32 v82, 0x4b800000, v81
	v_cmp_gt_f32_e32 vcc, s51, v81
	s_nop 1
	v_cndmask_b32_e32 v81, v81, v82, vcc
	v_rsq_f32_e32 v81, v81
	s_nop 0
	v_mul_f32_e32 v82, 0x45800000, v81
	v_cndmask_b32_e32 v82, v81, v82, vcc
	v_pk_mul_f32 v[76:77], v[76:77], v[82:83] op_sel_hi:[1,0]
	s_nop 0
	v_mul_f32_e32 v81, 0xbfb8aa3b, v76
	v_exp_f32_e32 v84, v81
	v_mul_f32_e32 v81, 0xbfb8aa3b, v77
	v_exp_f32_e32 v85, v81
	s_nop 0
	v_pk_add_f32 v[84:85], v[84:85], 1.0 op_sel_hi:[1,0]
	s_nop 0
	s_nop 0
	v_pk_mul_f32 v[72:73], v[72:73], v[82:83] op_sel_hi:[1,0]
	v_rcp_f32_e32 v85, v85
	v_pk_mul_f32 v[78:79], v[78:79], v[82:83] op_sel_hi:[1,0]
	v_mul_f32_e32 v86, 0xbfb8aa3b, v78
	v_mul_f32_e32 v87, 0xbfb8aa3b, v79
	v_exp_f32_e32 v86, v86
	v_exp_f32_e32 v87, v87
	v_rcp_f32_e32 v84, v84
	s_nop 0
	v_pk_mul_f32 v[76:77], v[76:77], v[84:85]
	v_pk_add_f32 v[86:87], v[86:87], 1.0 op_sel_hi:[1,0]
	v_pk_mul_f32 v[72:73], v[72:73], v[76:77]
	s_nop 0
	v_pk_mul_f32 v[74:75], v[74:75], v[82:83] op_sel_hi:[1,0]
	v_rcp_f32_e32 v77, v87
	v_pk_mul_f32 v[68:69], v[68:69], v[82:83] op_sel_hi:[1,0]
	v_mul_f32_e32 v81, 0xbfb8aa3b, v68
	v_exp_f32_e32 v84, v81
	v_mul_f32_e32 v81, 0xbfb8aa3b, v69
	v_exp_f32_e32 v85, v81
	v_rcp_f32_e32 v76, v86
	s_nop 0
	v_pk_mul_f32 v[76:77], v[78:79], v[76:77]
	v_pk_add_f32 v[84:85], v[84:85], 1.0 op_sel_hi:[1,0]
	v_pk_mul_f32 v[74:75], v[74:75], v[76:77]
	s_nop 0
	v_pk_mul_f32 v[64:65], v[64:65], v[82:83] op_sel_hi:[1,0]
	v_rcp_f32_e32 v77, v85
	v_pk_mul_f32 v[70:71], v[70:71], v[82:83] op_sel_hi:[1,0]
	v_mul_f32_e32 v78, 0xbfb8aa3b, v70
	v_mul_f32_e32 v79, 0xbfb8aa3b, v71
	v_exp_f32_e32 v78, v78
	v_exp_f32_e32 v79, v79
	v_rcp_f32_e32 v76, v84
	s_nop 0
	v_pk_mul_f32 v[68:69], v[68:69], v[76:77]
	v_pk_add_f32 v[78:79], v[78:79], 1.0 op_sel_hi:[1,0]
	v_pk_mul_f32 v[68:69], v[64:65], v[68:69]
	s_nop 0
	v_pk_mul_f32 v[64:65], v[66:67], v[82:83] op_sel_hi:[1,0]
	v_rcp_f32_e32 v67, v79
	v_rcp_f32_e32 v66, v78
	s_nop 0
	v_pk_mul_f32 v[66:67], v[70:71], v[66:67]
	s_nop 0
	v_pk_mul_f32 v[70:71], v[64:65], v[66:67]
	v_cvt_pk_bf16_f32 v66, v68, v69
	v_mad_i64_i32 v[68:69], s[0:1], v80, s52, v[112:113]
	v_cvt_pk_bf16_f32 v64, v72, v73
	v_cvt_pk_bf16_f32 v65, v74, v75
	v_cvt_pk_bf16_f32 v67, v70, v71
	v_lshl_add_u64 v[68:69], v[68:69], 0, v[114:115]
	global_store_dwordx4 v[68:69], v[64:67], off nt
	s_nop 0
	v_add_u32_e32 v70, 0x80, v144
	s_nop 0
	v_fmamk_f32 v64, v251, 0x3a800000, v158
	v_mul_f32_e32 v65, 0x4b800000, v64
	v_cmp_gt_f32_e32 vcc, s51, v64
	s_nop 1
	v_cndmask_b32_e32 v64, v64, v65, vcc
	v_rsq_f32_e32 v64, v64
	s_nop 0
	v_mul_f32_e32 v65, 0x45800000, v64
	v_cndmask_b32_e32 v64, v64, v65, vcc
	v_pk_mul_f32 v[60:61], v[60:61], v[64:65] op_sel_hi:[1,0]
	s_nop 0
	v_mul_f32_e32 v65, 0xbfb8aa3b, v60
	v_exp_f32_e32 v66, v65
; DI unsigned pk2(float lo, float hi) { f32x2_t v = {lo, hi}; bf16x2_t b = __builtin_convertvector(v, bf16x2_t); return __builtin_bit_cast(unsigned, b); }
; DI float sigmoidf_(float x) { return 1.0f / (1.0f + __expf(-x)); }
;     DI void operator()(AccRef acc, const Unit& u, int wr, int wc, int fr, int fq) const {
;     ...
;                 const int row = row0 + ai * HALF + m * 16; const float rs = rsqrtf(SS1[row] * (1.0f / DM) + EPSN);
;                 float h[8];
; #pragma unroll
;                 for (int n = 0; n < 2; ++n)
; #pragma unroll
;                     for (int e = 0; e < 4; ++e) { const float g = acc[ai][0][m][n][e] * rs, up = acc[ai][1][m][n][e] * rs; h[4 * n + e] = g * sigmoidf_(g) * up; }
;                 u32x4 w; w.x = pk2(h[0], h[1]); w.y = pk2(h[2], h[3]); w.z = pk2(h[4], h[5]); w.w = pk2(h[6], h[7]);
;                 *(u32x4*)(H + (size_t)row * DFF + col0) = w;
	v_mul_f32_e32 v65, 0xbfb8aa3b, v61
	v_exp_f32_e32 v67, v65
	s_nop 0
	v_pk_add_f32 v[66:67], v[66:67], 1.0 op_sel_hi:[1,0]
	s_nop 0
	v_pk_mul_f32 v[56:57], v[56:57], v[64:65] op_sel_hi:[1,0]
	v_rcp_f32_e32 v67, v67
	v_pk_mul_f32 v[62:63], v[62:63], v[64:65] op_sel_hi:[1,0]
	v_mul_f32_e32 v68, 0xbfb8aa3b, v62
	v_mul_f32_e32 v69, 0xbfb8aa3b, v63
	v_exp_f32_e32 v68, v68
	v_exp_f32_e32 v69, v69
	v_rcp_f32_e32 v66, v66
	s_nop 0
	v_pk_mul_f32 v[60:61], v[60:61], v[66:67]
	v_pk_add_f32 v[68:69], v[68:69], 1.0 op_sel_hi:[1,0]
	s_nop 0
	v_pk_mul_f32 v[56:57], v[56:57], v[60:61]
	v_pk_mul_f32 v[58:59], v[58:59], v[64:65] op_sel_hi:[1,0]
	v_rcp_f32_e32 v61, v69
	v_pk_mul_f32 v[52:53], v[52:53], v[64:65] op_sel_hi:[1,0]
	v_mul_f32_e32 v65, 0xbfb8aa3b, v52
	v_exp_f32_e32 v66, v65
	v_mul_f32_e32 v65, 0xbfb8aa3b, v53
	v_exp_f32_e32 v67, v65
	v_rcp_f32_e32 v60, v68
	s_nop 0
	v_pk_mul_f32 v[60:61], v[62:63], v[60:61]
	v_pk_add_f32 v[66:67], v[66:67], 1.0 op_sel_hi:[1,0]
	v_pk_mul_f32 v[58:59], v[58:59], v[60:61]
	v_pk_mul_f32 v[48:49], v[48:49], v[64:65] op_sel_hi:[1,0]
	v_rcp_f32_e32 v61, v67
	v_pk_mul_f32 v[54:55], v[54:55], v[64:65] op_sel_hi:[1,0]
	v_mul_f32_e32 v62, 0xbfb8aa3b, v54
	v_mul_f32_e32 v63, 0xbfb8aa3b, v55
	v_exp_f32_e32 v62, v62
	v_exp_f32_e32 v63, v63
	v_rcp_f32_e32 v60, v66
	s_nop 0
	v_pk_mul_f32 v[52:53], v[52:53], v[60:61]
	v_pk_add_f32 v[62:63], v[62:63], 1.0 op_sel_hi:[1,0]
	v_pk_mul_f32 v[52:53], v[48:49], v[52:53]
	v_pk_mul_f32 v[48:49], v[50:51], v[64:65] op_sel_hi:[1,0]
	v_rcp_f32_e32 v51, v63
	v_rcp_f32_e32 v50, v62
	s_nop 0
	v_pk_mul_f32 v[50:51], v[54:55], v[50:51]
	s_nop 0
	v_pk_mul_f32 v[54:55], v[48:49], v[50:51]
	v_cvt_pk_bf16_f32 v50, v52, v53
	v_mad_i64_i32 v[52:53], s[0:1], v70, s52, v[112:113]
	v_cvt_pk_bf16_f32 v48, v56, v57
	v_cvt_pk_bf16_f32 v49, v58, v59
	v_cvt_pk_bf16_f32 v51, v54, v55
	v_lshl_add_u64 v[52:53], v[52:53], 0, v[114:115]
	global_store_dwordx4 v[52:53], v[48:51], off nt
	s_nop 0
	v_add_u32_e32 v54, 0x90, v144
	s_nop 0
	v_fmamk_f32 v48, v252, 0x3a800000, v158
	v_mul_f32_e32 v49, 0x4b800000, v48
	v_cmp_gt_f32_e32 vcc, s51, v48
	s_nop 1
	v_cndmask_b32_e32 v48, v48, v49, vcc
	v_rsq_f32_e32 v48, v48
	s_nop 0
	v_mul_f32_e32 v49, 0x45800000, v48
	v_cndmask_b32_e32 v48, v48, v49, vcc
	v_pk_mul_f32 v[44:45], v[44:45], v[48:49] op_sel_hi:[1,0]
	s_nop 0
	v_mul_f32_e32 v49, 0xbfb8aa3b, v44
	v_exp_f32_e32 v50, v49
	v_mul_f32_e32 v49, 0xbfb8aa3b, v45
	v_exp_f32_e32 v51, v49
	s_nop 0
	v_pk_add_f32 v[50:51], v[50:51], 1.0 op_sel_hi:[1,0]
	s_nop 0
	v_pk_mul_f32 v[40:41], v[40:41], v[48:49] op_sel_hi:[1,0]
	v_rcp_f32_e32 v51, v51
	v_pk_mul_f32 v[46:47], v[46:47], v[48:49] op_sel_hi:[1,0]
	v_mul_f32_e32 v52, 0xbfb8aa3b, v46
	v_mul_f32_e32 v53, 0xbfb8aa3b, v47
	v_exp_f32_e32 v52, v52
	v_exp_f32_e32 v53, v53
	v_rcp_f32_e32 v50, v50
	s_nop 0
	v_pk_mul_f32 v[44:45], v[44:45], v[50:51]
	v_pk_add_f32 v[52:53], v[52:53], 1.0 op_sel_hi:[1,0]
	s_nop 0
	v_pk_mul_f32 v[40:41], v[40:41], v[44:45]
	v_pk_mul_f32 v[42:43], v[42:43], v[48:49] op_sel_hi:[1,0]
	v_rcp_f32_e32 v45, v53
	v_pk_mul_f32 v[36:37], v[36:37], v[48:49] op_sel_hi:[1,0]
	v_mul_f32_e32 v49, 0xbfb8aa3b, v36
	v_exp_f32_e32 v50, v49
	v_mul_f32_e32 v49, 0xbfb8aa3b, v37
	v_exp_f32_e32 v51, v49
	v_rcp_f32_e32 v44, v52
	s_nop 0
	v_pk_mul_f32 v[44:45], v[46:47], v[44:45]
	v_pk_add_f32 v[50:51], v[50:51], 1.0 op_sel_hi:[1,0]
	v_pk_mul_f32 v[42:43], v[42:43], v[44:45]
	v_pk_mul_f32 v[32:33], v[32:33], v[48:49] op_sel_hi:[1,0]
	v_rcp_f32_e32 v45, v51
	v_pk_mul_f32 v[38:39], v[38:39], v[48:49] op_sel_hi:[1,0]
	v_mul_f32_e32 v46, 0xbfb8aa3b, v38
	v_mul_f32_e32 v47, 0xbfb8aa3b, v39
	v_exp_f32_e32 v46, v46
	v_exp_f32_e32 v47, v47
	v_rcp_f32_e32 v44, v50
	s_nop 0
	v_pk_mul_f32 v[36:37], v[36:37], v[44:45]
	v_pk_add_f32 v[46:47], v[46:47], 1.0 op_sel_hi:[1,0]
	v_pk_mul_f32 v[36:37], v[32:33], v[36:37]
	v_pk_mul_f32 v[32:33], v[34:35], v[48:49] op_sel_hi:[1,0]
	v_rcp_f32_e32 v35, v47
	v_rcp_f32_e32 v34, v46
	s_nop 0
	v_pk_mul_f32 v[34:35], v[38:39], v[34:35]
	s_nop 0
	v_pk_mul_f32 v[38:39], v[32:33], v[34:35]
	v_cvt_pk_bf16_f32 v34, v36, v37
	v_mad_i64_i32 v[36:37], s[0:1], v54, s52, v[112:113]
	v_cvt_pk_bf16_f32 v32, v40, v41
	v_cvt_pk_bf16_f32 v33, v42, v43
	v_cvt_pk_bf16_f32 v35, v38, v39
	v_lshl_add_u64 v[36:37], v[36:37], 0, v[114:115]
	global_store_dwordx4 v[36:37], v[32:35], off nt
	s_nop 0
	v_add_u32_e32 v38, 0xa0, v144
	s_nop 0
	v_fmamk_f32 v32, v253, 0x3a800000, v158
	v_mul_f32_e32 v33, 0x4b800000, v32
	v_cmp_gt_f32_e32 vcc, s51, v32
	s_nop 1
	v_cndmask_b32_e32 v32, v32, v33, vcc
	v_rsq_f32_e32 v32, v32
	s_nop 0
	v_mul_f32_e32 v33, 0x45800000, v32
; #define PG8_BAR __builtin_amdgcn_s_barrier()
; DI unsigned pk2(float lo, float hi) { f32x2_t v = {lo, hi}; bf16x2_t b = __builtin_convertvector(v, bf16x2_t); return __builtin_bit_cast(unsigned, b); }
; DI float sigmoidf_(float x) { return 1.0f / (1.0f + __expf(-x)); }
; template <class Epi, class Sched, bool ALIGN_EPI = false, bool SP2 = false>
; __device__ __forceinline__ void gemm_phase(PG8_LAS unsigned char* lds, const Gemm g, const Sched& S, const Epi& E) {
;     ...
;         if (!has_next) break;
; #pragma unroll
;         for (int a = 0; a < 2; ++a)
; #pragma unroll
;             for (int b = 0; b < 2; ++b)
; #pragma unroll
;                 for (int m = 0; m < 4; ++m)
; #pragma unroll
;                     for (int n = 0; n < 2; ++n) acc[a][b][m][n] = (f32x4){0.f, 0.f, 0.f, 0.f};
;         cur = nxt; cA = nA; cB = nB; ++ui;
;         if constexpr (ALIGN_EPI) { if (wr == 1) PG8_BAR; }
;     DI void operator()(AccRef acc, const Unit& u, int wr, int wc, int fr, int fq) const {
;     ...
;                 const int row = row0 + ai * HALF + m * 16; const float rs = rsqrtf(SS1[row] * (1.0f / DM) + EPSN);
;                 float h[8];
; #pragma unroll
;                 for (int n = 0; n < 2; ++n)
; #pragma unroll
;                     for (int e = 0; e < 4; ++e) { const float g = acc[ai][0][m][n][e] * rs, up = acc[ai][1][m][n][e] * rs; h[4 * n + e] = g * sigmoidf_(g) * up; }
;                 u32x4 w; w.x = pk2(h[0], h[1]); w.y = pk2(h[2], h[3]); w.z = pk2(h[4], h[5]); w.w = pk2(h[6], h[7]);
;                 *(u32x4*)(H + (size_t)row * DFF + col0) = w;
	v_cndmask_b32_e32 v32, v32, v33, vcc
	v_pk_mul_f32 v[28:29], v[28:29], v[32:33] op_sel_hi:[1,0]
	s_nop 0
	v_mul_f32_e32 v33, 0xbfb8aa3b, v28
	v_exp_f32_e32 v34, v33
	v_mul_f32_e32 v33, 0xbfb8aa3b, v29
	v_exp_f32_e32 v35, v33
	s_nop 0
	v_pk_add_f32 v[34:35], v[34:35], 1.0 op_sel_hi:[1,0]
	s_nop 0
	v_pk_mul_f32 v[24:25], v[24:25], v[32:33] op_sel_hi:[1,0]
	v_rcp_f32_e32 v35, v35
	v_pk_mul_f32 v[30:31], v[30:31], v[32:33] op_sel_hi:[1,0]
	v_mul_f32_e32 v36, 0xbfb8aa3b, v30
	v_mul_f32_e32 v37, 0xbfb8aa3b, v31
	v_exp_f32_e32 v36, v36
	v_exp_f32_e32 v37, v37
	v_rcp_f32_e32 v34, v34
	s_nop 0
	v_pk_mul_f32 v[28:29], v[28:29], v[34:35]
	v_pk_add_f32 v[36:37], v[36:37], 1.0 op_sel_hi:[1,0]
	s_nop 0
	v_pk_mul_f32 v[24:25], v[24:25], v[28:29]
	v_pk_mul_f32 v[26:27], v[26:27], v[32:33] op_sel_hi:[1,0]
	v_rcp_f32_e32 v29, v37
	v_pk_mul_f32 v[20:21], v[20:21], v[32:33] op_sel_hi:[1,0]
	v_mul_f32_e32 v33, 0xbfb8aa3b, v20
	v_exp_f32_e32 v34, v33
	v_mul_f32_e32 v33, 0xbfb8aa3b, v21
	v_exp_f32_e32 v35, v33
	v_rcp_f32_e32 v28, v36
	s_nop 0
	v_pk_mul_f32 v[28:29], v[30:31], v[28:29]
	v_pk_add_f32 v[34:35], v[34:35], 1.0 op_sel_hi:[1,0]
	v_pk_mul_f32 v[26:27], v[26:27], v[28:29]
	v_pk_mul_f32 v[16:17], v[16:17], v[32:33] op_sel_hi:[1,0]
	v_rcp_f32_e32 v29, v35
	v_pk_mul_f32 v[22:23], v[22:23], v[32:33] op_sel_hi:[1,0]
	v_mul_f32_e32 v30, 0xbfb8aa3b, v22
	v_mul_f32_e32 v31, 0xbfb8aa3b, v23
	v_exp_f32_e32 v30, v30
	v_exp_f32_e32 v31, v31
	v_rcp_f32_e32 v28, v34
	s_nop 0
	v_pk_mul_f32 v[20:21], v[20:21], v[28:29]
	v_pk_add_f32 v[30:31], v[30:31], 1.0 op_sel_hi:[1,0]
	v_pk_mul_f32 v[20:21], v[16:17], v[20:21]
	v_pk_mul_f32 v[16:17], v[18:19], v[32:33] op_sel_hi:[1,0]
	v_rcp_f32_e32 v19, v31
	v_rcp_f32_e32 v18, v30
	s_nop 0
	v_pk_mul_f32 v[18:19], v[22:23], v[18:19]
	s_nop 0
	v_pk_mul_f32 v[22:23], v[16:17], v[18:19]
	v_cvt_pk_bf16_f32 v18, v20, v21
	v_mad_i64_i32 v[20:21], s[0:1], v38, s52, v[112:113]
	v_cvt_pk_bf16_f32 v16, v24, v25
	v_cvt_pk_bf16_f32 v17, v26, v27
	v_cvt_pk_bf16_f32 v19, v22, v23
	v_lshl_add_u64 v[20:21], v[20:21], 0, v[114:115]
	global_store_dwordx4 v[20:21], v[16:19], off nt
	s_nop 0
	v_add_u32_e32 v22, 0xb0, v144
	s_nop 0
	v_fmamk_f32 v16, v254, 0x3a800000, v158
	v_mul_f32_e32 v17, 0x4b800000, v16
	v_cmp_gt_f32_e32 vcc, s51, v16
	s_nop 1
	v_cndmask_b32_e32 v16, v16, v17, vcc
	v_rsq_f32_e32 v16, v16
	s_nop 0
	v_mul_f32_e32 v17, 0x45800000, v16
	v_cndmask_b32_e32 v16, v16, v17, vcc
	v_pk_mul_f32 v[12:13], v[12:13], v[16:17] op_sel_hi:[1,0]
	s_nop 0
	v_mul_f32_e32 v17, 0xbfb8aa3b, v12
	v_exp_f32_e32 v18, v17
	v_mul_f32_e32 v17, 0xbfb8aa3b, v13
	v_exp_f32_e32 v19, v17
	s_nop 0
	v_pk_add_f32 v[18:19], v[18:19], 1.0 op_sel_hi:[1,0]
	s_nop 0
	v_pk_mul_f32 v[8:9], v[8:9], v[16:17] op_sel_hi:[1,0]
	v_rcp_f32_e32 v19, v19
	v_pk_mul_f32 v[14:15], v[14:15], v[16:17] op_sel_hi:[1,0]
	v_mul_f32_e32 v20, 0xbfb8aa3b, v14
	v_mul_f32_e32 v21, 0xbfb8aa3b, v15
	v_exp_f32_e32 v20, v20
	v_exp_f32_e32 v21, v21
	v_rcp_f32_e32 v18, v18
	s_nop 0
	v_pk_mul_f32 v[12:13], v[12:13], v[18:19]
	v_pk_add_f32 v[20:21], v[20:21], 1.0 op_sel_hi:[1,0]
	s_nop 0
	v_pk_mul_f32 v[8:9], v[8:9], v[12:13]
	v_pk_mul_f32 v[10:11], v[10:11], v[16:17] op_sel_hi:[1,0]
	v_rcp_f32_e32 v13, v21
	v_pk_mul_f32 v[4:5], v[4:5], v[16:17] op_sel_hi:[1,0]
	v_mul_f32_e32 v17, 0xbfb8aa3b, v4
	v_exp_f32_e32 v18, v17
	v_mul_f32_e32 v17, 0xbfb8aa3b, v5
	v_exp_f32_e32 v19, v17
	v_rcp_f32_e32 v12, v20
	s_nop 0
	v_pk_mul_f32 v[12:13], v[14:15], v[12:13]
	v_pk_add_f32 v[18:19], v[18:19], 1.0 op_sel_hi:[1,0]
	v_pk_mul_f32 v[10:11], v[10:11], v[12:13]
	v_pk_mul_f32 v[0:1], v[0:1], v[16:17] op_sel_hi:[1,0]
	v_rcp_f32_e32 v13, v19
	v_pk_mul_f32 v[6:7], v[6:7], v[16:17] op_sel_hi:[1,0]
	v_mul_f32_e32 v14, 0xbfb8aa3b, v6
	v_mul_f32_e32 v15, 0xbfb8aa3b, v7
	v_exp_f32_e32 v14, v14
	v_exp_f32_e32 v15, v15
	v_rcp_f32_e32 v12, v18
	s_nop 0
	v_pk_mul_f32 v[4:5], v[4:5], v[12:13]
	v_pk_add_f32 v[14:15], v[14:15], 1.0 op_sel_hi:[1,0]
	v_pk_mul_f32 v[4:5], v[0:1], v[4:5]
	v_pk_mul_f32 v[0:1], v[2:3], v[16:17] op_sel_hi:[1,0]
	v_rcp_f32_e32 v3, v15
	v_rcp_f32_e32 v2, v14
	s_nop 0
	v_pk_mul_f32 v[2:3], v[6:7], v[2:3]
	s_andn2_b64 vcc, exec, s[2:3]
	v_pk_mul_f32 v[6:7], v[0:1], v[2:3]
	v_cvt_pk_bf16_f32 v2, v4, v5
	v_mad_i64_i32 v[4:5], s[0:1], v22, s52, v[112:113]
	v_cvt_pk_bf16_f32 v0, v8, v9
	v_cvt_pk_bf16_f32 v1, v10, v11
	v_cvt_pk_bf16_f32 v3, v6, v7
	v_lshl_add_u64 v[4:5], v[4:5], 0, v[114:115]
	s_mov_b64 s[0:1], -1
	global_store_dwordx4 v[4:5], v[0:3], off nt
	s_cbranch_vccnz .LBB0_1662
	s_andn2_b64 vcc, exec, s[16:17]
	s_cbranch_vccnz .LBB0_1661
	s_barrier
	s_branch .LBB0_1661
